# stagger step halved (0..2.25us over 4 workgroup groups)
# speedup vs baseline: 1.0314x; 1.0070x over previous
; #define REPS(k) for (int rep = 0; rep < ((DUP_PHASE == (k)) ? 2 : 1); ++rep)
; __global__ void __launch_bounds__(NT, 2) fwd(Args args) {
;     ...
;     if (IN(1)) REPS(1) {
;         pg8::Gemm g{AH, WT_IN, MA, NBT, D}; SchedIn S{G, bx, (unsigned*)(ctl + CW_EA), bar.x, bar.st};
;         EpiIn E{CB, UB, QB, KB, VB, MQB, GB, MKB, MVB, out};
;         pg8::gemm_phase<EpiIn, SchedIn, true, true>(lds, g, S, E);
.Lstag:
	s_cmp_eq_u32 s40, 0
	s_cbranch_scc1 .Lstag_done
	s_sleep 24
	s_sub_u32 s40, s40, 1
	s_branch .Lstag
